# removed the per-tile s_waitcnt vmcnt(0) store drain before the QKV and LN K-loops (counted in-loop waits stay conservative)
# baseline (speedup 1.0000x reference)
.LBB0_123:
	s_ashr_i32 s23, s22, 31
	s_lshl_b64 s[24:25], s[22:23], 19
	s_add_u32 s24, s12, s24
	s_addc_u32 s25, s13, s25
	s_and_b64 s[26:27], s[6:7], exec
	s_cselect_b32 s23, s25, s35
	s_cselect_b32 s29, s24, s34
	s_ashr_i32 s21, s20, 31
	s_lshl_b64 s[26:27], s[20:21], 19
	s_add_u32 s26, s10, s26
	s_addc_u32 s27, s11, s27
	s_and_b64 s[36:37], s[6:7], exec
	s_cselect_b32 s21, s27, s9
	s_cselect_b32 s31, s26, s8
	s_add_u32 s46, s8, 0x100
	s_addc_u32 s47, s9, 0
	s_add_u32 s8, s34, 0x40080
	s_addc_u32 s9, s35, 0
	s_mov_b32 s48, -2
	s_add_u32 s34, s8, 0xfffc0080
	s_addc_u32 s35, s9, -1
	s_add_i32 s49, 0, 0x10000
	s_cmp_eq_u32 s48, 12
	s_cselect_b32 s37, s23, s35
	s_cselect_b32 s36, s29, s34
	s_cselect_b32 s35, s21, s47
	s_cselect_b32 s34, s31, s46
	s_add_i32 s52, 0, 0x14000
	v_add_u32_e32 v76, s49, v233
	v_add_u32_e32 v132, s52, v233
	ds_read_b128 v[56:59], v76
	ds_read_b128 v[60:63], v76 offset:1024
	ds_read_b128 v[68:71], v76 offset:2048
	ds_read_b128 v[76:79], v76 offset:3072
	ds_read_b128 v[104:107], v132
	ds_read_b128 v[108:111], v132 offset:1024
	ds_read_b128 v[124:127], v132 offset:2048
	ds_read_b128 v[132:135], v132 offset:3072
	v_lshl_add_u64 v[208:209], s[8:9], 0, v[206:207]
	s_add_i32 m0, s39, 0xc000
	ds_read_b128 v[152:155], v235
	ds_read_b128 v[156:159], v235 offset:1024
	ds_read_b128 v[168:171], v235 offset:2048
	ds_read_b128 v[172:175], v235 offset:3072
	ds_read_b128 v[176:179], v235 offset:4096
	ds_read_b128 v[180:183], v235 offset:5120
	ds_read_b128 v[184:187], v235 offset:6144
	ds_read_b128 v[188:191], v235 offset:7168
	global_load_lds_dwordx4 v[208:209], off
	v_lshl_add_u64 v[208:209], s[8:9], 0, v[204:205]
	s_add_i32 m0, s39, 0xe000
	s_nop 0
	global_load_lds_dwordx4 v[208:209], off
	s_waitcnt vmcnt(8)
	s_waitcnt lgkmcnt(0)
	s_barrier
	s_setprio 1
	s_waitcnt lgkmcnt(0)
	v_mfma_f32_16x16x32_bf16 v[164:167], v[56:59], v[152:155], 0
	v_mfma_f32_16x16x32_bf16 v[160:163], v[68:71], v[152:155], 0
	v_mfma_f32_16x16x32_bf16 v[140:143], v[56:59], v[168:171], 0
	v_mfma_f32_16x16x32_bf16 v[136:139], v[68:71], v[168:171], 0
	v_mfma_f32_16x16x32_bf16 v[116:119], v[56:59], v[176:179], 0
	v_mfma_f32_16x16x32_bf16 v[112:115], v[68:71], v[176:179], 0
	v_mfma_f32_16x16x32_bf16 v[92:95], v[56:59], v[184:187], 0
	v_mfma_f32_16x16x32_bf16 v[88:91], v[68:71], v[184:187], 0
	v_mfma_f32_16x16x32_bf16 v[164:167], v[60:63], v[156:159], v[164:167]
	v_mfma_f32_16x16x32_bf16 v[160:163], v[76:79], v[156:159], v[160:163]
	v_mfma_f32_16x16x32_bf16 v[140:143], v[60:63], v[172:175], v[140:143]
	v_mfma_f32_16x16x32_bf16 v[136:139], v[76:79], v[172:175], v[136:139]
	v_mfma_f32_16x16x32_bf16 v[116:119], v[60:63], v[180:183], v[116:119]
	v_mfma_f32_16x16x32_bf16 v[112:115], v[76:79], v[180:183], v[112:115]
	v_mfma_f32_16x16x32_bf16 v[92:95], v[60:63], v[188:191], v[92:95]
	v_mfma_f32_16x16x32_bf16 v[88:91], v[76:79], v[188:191], v[88:91]
	s_setprio 0
	s_setprio 1
	v_mfma_f32_16x16x32_bf16 v[148:151], v[104:107], v[152:155], 0
	v_mfma_f32_16x16x32_bf16 v[144:147], v[124:127], v[152:155], 0
	v_mfma_f32_16x16x32_bf16 v[128:131], v[104:107], v[168:171], 0
	v_mfma_f32_16x16x32_bf16 v[120:123], v[124:127], v[168:171], 0
	v_mfma_f32_16x16x32_bf16 v[100:103], v[104:107], v[176:179], 0
	v_mfma_f32_16x16x32_bf16 v[96:99], v[124:127], v[176:179], 0
	v_mfma_f32_16x16x32_bf16 v[84:87], v[104:107], v[184:187], 0
	v_mfma_f32_16x16x32_bf16 v[80:83], v[124:127], v[184:187], 0
	v_mfma_f32_16x16x32_bf16 v[148:151], v[108:111], v[156:159], v[148:151]
	v_mfma_f32_16x16x32_bf16 v[144:147], v[132:135], v[156:159], v[144:147]
	v_mfma_f32_16x16x32_bf16 v[128:131], v[108:111], v[172:175], v[128:131]
	v_mfma_f32_16x16x32_bf16 v[120:123], v[132:135], v[172:175], v[120:123]
	v_mfma_f32_16x16x32_bf16 v[100:103], v[108:111], v[180:183], v[100:103]
	v_mfma_f32_16x16x32_bf16 v[96:99], v[132:135], v[180:183], v[96:99]
	v_mfma_f32_16x16x32_bf16 v[84:87], v[108:111], v[188:191], v[84:87]
	v_mfma_f32_16x16x32_bf16 v[80:83], v[132:135], v[188:191], v[80:83]
	s_setprio 0
	s_barrier
	s_nop 0
	s_add_i32 s49, s49, s38
	v_lshl_add_u64 v[208:209], s[34:35], 0, v[192:193]
	s_mov_b32 m0, s49
	ds_read_b128 v[152:155], v235 offset:16384
	ds_read_b128 v[156:159], v235 offset:17408
	ds_read_b128 v[168:171], v235 offset:18432
	ds_read_b128 v[172:175], v235 offset:19456
	ds_read_b128 v[176:179], v235 offset:20480
	ds_read_b128 v[180:183], v235 offset:21504
	ds_read_b128 v[184:187], v235 offset:22528
	ds_read_b128 v[188:191], v235 offset:23552
	global_load_lds_dwordx4 v[208:209], off
	s_add_i32 m0, s49, 0x2000
	s_add_u32 s50, s34, 0x40000
	v_lshl_add_u64 v[210:211], s[34:35], 0, v[200:201]
	s_addc_u32 s51, s35, 0
	s_add_i32 s49, s52, s38
	global_load_lds_dwordx4 v[210:211], off
	v_lshl_add_u64 v[212:213], s[50:51], 0, v[192:193]
	s_mov_b32 m0, s49
	v_lshl_add_u64 v[214:215], s[36:37], 0, v[198:199]
	global_load_lds_dwordx4 v[212:213], off
	v_lshl_add_u64 v[212:213], s[50:51], 0, v[200:201]
	s_add_i32 m0, s49, 0x2000
	s_nop 0
	global_load_lds_dwordx4 v[212:213], off
	v_lshl_add_u64 v[212:213], s[36:37], 0, v[196:197]
	s_mov_b32 m0, s39
	s_nop 0
	global_load_lds_dwordx4 v[212:213], off
	s_mov_b32 m0, s40
	s_nop 0
	global_load_lds_dwordx4 v[214:215], off
	s_waitcnt vmcnt(8)
	s_waitcnt lgkmcnt(0)
	s_barrier
	s_setprio 1
	s_waitcnt lgkmcnt(0)
	v_mfma_f32_16x16x32_bf16 v[72:75], v[56:59], v[152:155], 0
	v_mfma_f32_16x16x32_bf16 v[64:67], v[68:71], v[152:155], 0
	v_mfma_f32_16x16x32_bf16 v[44:47], v[56:59], v[168:171], 0
	v_mfma_f32_16x16x32_bf16 v[40:43], v[68:71], v[168:171], 0
	v_mfma_f32_16x16x32_bf16 v[28:31], v[56:59], v[176:179], 0
	v_mfma_f32_16x16x32_bf16 v[24:27], v[68:71], v[176:179], 0
	v_mfma_f32_16x16x32_bf16 v[12:15], v[56:59], v[184:187], 0
	v_mfma_f32_16x16x32_bf16 v[8:11], v[68:71], v[184:187], 0
	v_mfma_f32_16x16x32_bf16 v[72:75], v[60:63], v[156:159], v[72:75]
	v_mfma_f32_16x16x32_bf16 v[64:67], v[76:79], v[156:159], v[64:67]
	v_mfma_f32_16x16x32_bf16 v[44:47], v[60:63], v[172:175], v[44:47]
	v_mfma_f32_16x16x32_bf16 v[40:43], v[76:79], v[172:175], v[40:43]
	v_mfma_f32_16x16x32_bf16 v[28:31], v[60:63], v[180:183], v[28:31]
	v_mfma_f32_16x16x32_bf16 v[24:27], v[76:79], v[180:183], v[24:27]
	v_mfma_f32_16x16x32_bf16 v[12:15], v[60:63], v[188:191], v[12:15]
	v_mfma_f32_16x16x32_bf16 v[8:11], v[76:79], v[188:191], v[8:11]
	s_setprio 0
	s_setprio 1
	v_mfma_f32_16x16x32_bf16 v[52:55], v[104:107], v[152:155], 0
	v_mfma_f32_16x16x32_bf16 v[48:51], v[124:127], v[152:155], 0
	v_mfma_f32_16x16x32_bf16 v[36:39], v[104:107], v[168:171], 0
	v_mfma_f32_16x16x32_bf16 v[32:35], v[124:127], v[168:171], 0
	v_mfma_f32_16x16x32_bf16 v[20:23], v[104:107], v[176:179], 0
	v_mfma_f32_16x16x32_bf16 v[16:19], v[124:127], v[176:179], 0
	v_mfma_f32_16x16x32_bf16 v[4:7], v[104:107], v[184:187], 0
	v_mfma_f32_16x16x32_bf16 v[0:3], v[124:127], v[184:187], 0
	v_mfma_f32_16x16x32_bf16 v[52:55], v[108:111], v[156:159], v[52:55]
	v_mfma_f32_16x16x32_bf16 v[48:51], v[132:135], v[156:159], v[48:51]
	v_mfma_f32_16x16x32_bf16 v[36:39], v[108:111], v[172:175], v[36:39]
	v_mfma_f32_16x16x32_bf16 v[32:35], v[132:135], v[172:175], v[32:35]
	v_mfma_f32_16x16x32_bf16 v[20:23], v[108:111], v[180:183], v[20:23]
	v_mfma_f32_16x16x32_bf16 v[16:19], v[132:135], v[180:183], v[16:19]
	v_mfma_f32_16x16x32_bf16 v[4:7], v[108:111], v[188:191], v[4:7]
	v_mfma_f32_16x16x32_bf16 v[0:3], v[132:135], v[188:191], v[0:3]
	s_setprio 0
	s_barrier
	s_nop 0
	s_add_i32 s49, 0, 0x18000
	s_add_i32 s50, 0, 0x1c000
	v_add_u32_e32 v76, s49, v233
	v_add_u32_e32 v132, s50, v233
	ds_read_b128 v[56:59], v76
	ds_read_b128 v[60:63], v76 offset:1024
	ds_read_b128 v[68:71], v76 offset:2048
	ds_read_b128 v[76:79], v76 offset:3072
	ds_read_b128 v[104:107], v132
	ds_read_b128 v[108:111], v132 offset:1024
	ds_read_b128 v[124:127], v132 offset:2048
	ds_read_b128 v[132:135], v132 offset:3072
	s_add_u32 s36, s36, 0x40000
	s_addc_u32 s37, s37, 0
	s_mov_b32 m0, s41
	v_lshl_add_u64 v[216:217], s[36:37], 0, v[196:197]
	ds_read_b128 v[152:155], v235 offset:32768
	ds_read_b128 v[156:159], v235 offset:33792
	ds_read_b128 v[168:171], v235 offset:34816
	ds_read_b128 v[172:175], v235 offset:35840
	ds_read_b128 v[176:179], v235 offset:36864
	ds_read_b128 v[180:183], v235 offset:37888
	ds_read_b128 v[184:187], v235 offset:38912
	ds_read_b128 v[188:191], v235 offset:39936
	global_load_lds_dwordx4 v[216:217], off
	v_lshl_add_u64 v[216:217], s[36:37], 0, v[198:199]
	s_mov_b32 m0, s42
	s_nop 0
	global_load_lds_dwordx4 v[216:217], off
	s_waitcnt vmcnt(8)
	s_waitcnt lgkmcnt(0)
	s_barrier
	s_setprio 1
	s_waitcnt lgkmcnt(0)
	v_mfma_f32_16x16x32_bf16 v[164:167], v[56:59], v[152:155], v[164:167]
	v_mfma_f32_16x16x32_bf16 v[160:163], v[68:71], v[152:155], v[160:163]
	v_mfma_f32_16x16x32_bf16 v[140:143], v[56:59], v[168:171], v[140:143]
	v_mfma_f32_16x16x32_bf16 v[136:139], v[68:71], v[168:171], v[136:139]
	v_mfma_f32_16x16x32_bf16 v[116:119], v[56:59], v[176:179], v[116:119]
	v_mfma_f32_16x16x32_bf16 v[112:115], v[68:71], v[176:179], v[112:115]
	v_mfma_f32_16x16x32_bf16 v[92:95], v[56:59], v[184:187], v[92:95]
	v_mfma_f32_16x16x32_bf16 v[88:91], v[68:71], v[184:187], v[88:91]
	v_mfma_f32_16x16x32_bf16 v[164:167], v[60:63], v[156:159], v[164:167]
	v_mfma_f32_16x16x32_bf16 v[160:163], v[76:79], v[156:159], v[160:163]
	v_mfma_f32_16x16x32_bf16 v[140:143], v[60:63], v[172:175], v[140:143]
	v_mfma_f32_16x16x32_bf16 v[136:139], v[76:79], v[172:175], v[136:139]
	v_mfma_f32_16x16x32_bf16 v[116:119], v[60:63], v[180:183], v[116:119]
	v_mfma_f32_16x16x32_bf16 v[112:115], v[76:79], v[180:183], v[112:115]
	v_mfma_f32_16x16x32_bf16 v[92:95], v[60:63], v[188:191], v[92:95]
	v_mfma_f32_16x16x32_bf16 v[88:91], v[76:79], v[188:191], v[88:91]
	s_setprio 0
	s_setprio 1
	v_mfma_f32_16x16x32_bf16 v[148:151], v[104:107], v[152:155], v[148:151]
	v_mfma_f32_16x16x32_bf16 v[144:147], v[124:127], v[152:155], v[144:147]
	v_mfma_f32_16x16x32_bf16 v[128:131], v[104:107], v[168:171], v[128:131]
	v_mfma_f32_16x16x32_bf16 v[120:123], v[124:127], v[168:171], v[120:123]
	v_mfma_f32_16x16x32_bf16 v[100:103], v[104:107], v[176:179], v[100:103]
	v_mfma_f32_16x16x32_bf16 v[96:99], v[124:127], v[176:179], v[96:99]
	v_mfma_f32_16x16x32_bf16 v[84:87], v[104:107], v[184:187], v[84:87]
	v_mfma_f32_16x16x32_bf16 v[80:83], v[124:127], v[184:187], v[80:83]
	v_mfma_f32_16x16x32_bf16 v[148:151], v[108:111], v[156:159], v[148:151]
	v_mfma_f32_16x16x32_bf16 v[144:147], v[132:135], v[156:159], v[144:147]
	v_mfma_f32_16x16x32_bf16 v[128:131], v[108:111], v[172:175], v[128:131]
	v_mfma_f32_16x16x32_bf16 v[120:123], v[132:135], v[172:175], v[120:123]
	v_mfma_f32_16x16x32_bf16 v[100:103], v[108:111], v[180:183], v[100:103]
	v_mfma_f32_16x16x32_bf16 v[96:99], v[132:135], v[180:183], v[96:99]
	v_mfma_f32_16x16x32_bf16 v[84:87], v[108:111], v[188:191], v[84:87]
	v_mfma_f32_16x16x32_bf16 v[80:83], v[132:135], v[188:191], v[80:83]
	s_setprio 0
	s_barrier
	s_add_i32 s36, s49, s38
	v_lshl_add_u64 v[208:209], v[208:209], 0, s[2:3]
	s_mov_b32 m0, s36
	ds_read_b128 v[152:155], v235 offset:49152
	ds_read_b128 v[156:159], v235 offset:50176
	ds_read_b128 v[168:171], v235 offset:51200
	ds_read_b128 v[172:175], v235 offset:52224
	ds_read_b128 v[176:179], v235 offset:53248
	ds_read_b128 v[180:183], v235 offset:54272
	ds_read_b128 v[184:187], v235 offset:55296
	ds_read_b128 v[188:191], v235 offset:56320
	global_load_lds_dwordx4 v[208:209], off
	s_add_i32 m0, s36, 0x2000
	s_add_u32 s34, s34, 0x40080
	v_lshl_add_u64 v[208:209], v[210:211], 0, s[2:3]
	s_addc_u32 s35, s35, 0
	s_add_i32 s36, s50, s38
	global_load_lds_dwordx4 v[208:209], off
	v_lshl_add_u64 v[208:209], s[34:35], 0, v[192:193]
	s_mov_b32 m0, s36
	s_nop 0
	global_load_lds_dwordx4 v[208:209], off
	v_lshl_add_u64 v[208:209], s[34:35], 0, v[200:201]
	s_add_i32 m0, s36, 0x2000
	s_nop 0
	global_load_lds_dwordx4 v[208:209], off
	v_lshl_add_u64 v[208:209], v[212:213], 0, s[2:3]
	s_mov_b32 m0, s43
	s_nop 0
	global_load_lds_dwordx4 v[208:209], off
	v_lshl_add_u64 v[208:209], v[214:215], 0, s[2:3]
	s_mov_b32 m0, s44
	s_nop 0
	global_load_lds_dwordx4 v[208:209], off
	s_waitcnt vmcnt(8)
	s_waitcnt lgkmcnt(0)
	s_barrier
	s_setprio 1
	s_waitcnt lgkmcnt(0)
	v_mfma_f32_16x16x32_bf16 v[72:75], v[56:59], v[152:155], v[72:75]
	v_mfma_f32_16x16x32_bf16 v[64:67], v[68:71], v[152:155], v[64:67]
	v_mfma_f32_16x16x32_bf16 v[44:47], v[56:59], v[168:171], v[44:47]
	v_mfma_f32_16x16x32_bf16 v[40:43], v[68:71], v[168:171], v[40:43]
	v_mfma_f32_16x16x32_bf16 v[28:31], v[56:59], v[176:179], v[28:31]
	v_mfma_f32_16x16x32_bf16 v[24:27], v[68:71], v[176:179], v[24:27]
	v_mfma_f32_16x16x32_bf16 v[12:15], v[56:59], v[184:187], v[12:15]
	v_mfma_f32_16x16x32_bf16 v[8:11], v[68:71], v[184:187], v[8:11]
	v_mfma_f32_16x16x32_bf16 v[72:75], v[60:63], v[156:159], v[72:75]
	v_mfma_f32_16x16x32_bf16 v[64:67], v[76:79], v[156:159], v[64:67]
	v_mfma_f32_16x16x32_bf16 v[44:47], v[60:63], v[172:175], v[44:47]
	v_mfma_f32_16x16x32_bf16 v[40:43], v[76:79], v[172:175], v[40:43]
	v_mfma_f32_16x16x32_bf16 v[28:31], v[60:63], v[180:183], v[28:31]
	v_mfma_f32_16x16x32_bf16 v[24:27], v[76:79], v[180:183], v[24:27]
	v_mfma_f32_16x16x32_bf16 v[12:15], v[60:63], v[188:191], v[12:15]
	v_mfma_f32_16x16x32_bf16 v[8:11], v[76:79], v[188:191], v[8:11]
	s_setprio 0
	s_setprio 1
	v_mfma_f32_16x16x32_bf16 v[52:55], v[104:107], v[152:155], v[52:55]
	v_mfma_f32_16x16x32_bf16 v[48:51], v[124:127], v[152:155], v[48:51]
	v_mfma_f32_16x16x32_bf16 v[36:39], v[104:107], v[168:171], v[36:39]
	v_mfma_f32_16x16x32_bf16 v[32:35], v[124:127], v[168:171], v[32:35]
	v_mfma_f32_16x16x32_bf16 v[20:23], v[104:107], v[176:179], v[20:23]
	v_mfma_f32_16x16x32_bf16 v[16:19], v[124:127], v[176:179], v[16:19]
	v_mfma_f32_16x16x32_bf16 v[4:7], v[104:107], v[184:187], v[4:7]
	v_mfma_f32_16x16x32_bf16 v[0:3], v[124:127], v[184:187], v[0:3]
	v_mfma_f32_16x16x32_bf16 v[52:55], v[108:111], v[156:159], v[52:55]
	v_mfma_f32_16x16x32_bf16 v[48:51], v[132:135], v[156:159], v[48:51]
	v_mfma_f32_16x16x32_bf16 v[36:39], v[108:111], v[172:175], v[36:39]
	v_mfma_f32_16x16x32_bf16 v[32:35], v[132:135], v[172:175], v[32:35]
	v_mfma_f32_16x16x32_bf16 v[20:23], v[108:111], v[180:183], v[20:23]
	v_mfma_f32_16x16x32_bf16 v[16:19], v[132:135], v[180:183], v[16:19]
	v_mfma_f32_16x16x32_bf16 v[4:7], v[108:111], v[188:191], v[4:7]
	v_mfma_f32_16x16x32_bf16 v[0:3], v[132:135], v[188:191], v[0:3]
	s_setprio 0
	s_barrier
	s_add_i32 s48, s48, 2
	s_add_u32 s46, s46, 0x100
	s_addc_u32 s47, s47, 0
	s_add_u32 s8, s8, 0x100
	s_addc_u32 s9, s9, 0
	s_cmp_gt_u32 s48, 13
	s_cbranch_scc0 .LBB0_124
	s_branch .Lpeel_exit_124

.LBB0_667:
	s_add_u32 s51, s52, 0x100
	s_addc_u32 s74, s53, 0
	s_add_u32 s12, s54, 0x80
	s_addc_u32 s13, s55, 0
	s_mov_b32 s52, 0
	s_nop 0
	s_add_i32 s54, s52, 2
	s_add_u32 s55, s12, 0x80
	s_addc_u32 s53, s13, 0
	s_add_i32 s75, 0, 0x10000
	s_cmp_eq_u32 s73, s52
	s_cselect_b32 s53, s47, s53
	s_cselect_b32 s52, s46, s55
	s_cselect_b32 s83, s49, s74
	s_cselect_b32 s82, s48, s51
	s_add_i32 s55, 0, 0x14000
	v_add_u32_e32 v140, s75, v203
	v_add_u32_e32 v156, s55, v203
	ds_read_b128 v[128:131], v140
	ds_read_b128 v[132:135], v140 offset:1024
	ds_read_b128 v[136:139], v140 offset:2048
	ds_read_b128 v[140:143], v140 offset:3072
	ds_read_b128 v[144:147], v156
	ds_read_b128 v[148:151], v156 offset:1024
	ds_read_b128 v[152:155], v156 offset:2048
	ds_read_b128 v[156:159], v156 offset:3072
	v_lshl_add_u64 v[190:191], s[12:13], 0, v[184:185]
	s_add_i32 m0, s63, 0xc000
	ds_read_b128 v[160:163], v231
	ds_read_b128 v[164:167], v231 offset:1024
	ds_read_b128 v[168:171], v231 offset:2048
	ds_read_b128 v[172:175], v231 offset:3072
	ds_read_b128 v[186:189], v231 offset:4096
	ds_read_b128 v[196:199], v231 offset:5120
	ds_read_b128 v[224:227], v231 offset:6144
	ds_read_b128 v[238:241], v231 offset:7168
	global_load_lds_dwordx4 v[190:191], off
	v_lshl_add_u64 v[190:191], s[12:13], 0, v[182:183]
	s_add_i32 m0, s63, 0xe000
	s_nop 0
	global_load_lds_dwordx4 v[190:191], off
	s_waitcnt vmcnt(8)
	s_waitcnt lgkmcnt(0)
	s_barrier
	s_setprio 1
	s_waitcnt lgkmcnt(0)
	v_mfma_f32_16x16x32_bf16 v[68:71], v[128:131], v[160:163], 0
	v_mfma_f32_16x16x32_bf16 v[72:75], v[136:139], v[160:163], 0
	v_mfma_f32_16x16x32_bf16 v[8:11], v[128:131], v[168:171], 0
	v_mfma_f32_16x16x32_bf16 v[16:19], v[136:139], v[168:171], 0
	v_mfma_f32_16x16x32_bf16 v[56:59], v[128:131], v[186:189], 0
	v_mfma_f32_16x16x32_bf16 v[60:63], v[136:139], v[186:189], 0
	v_mfma_f32_16x16x32_bf16 v[36:39], v[128:131], v[224:227], 0
	v_mfma_f32_16x16x32_bf16 v[44:47], v[136:139], v[224:227], 0
	v_mfma_f32_16x16x32_bf16 v[68:71], v[132:135], v[164:167], v[68:71]
	v_mfma_f32_16x16x32_bf16 v[72:75], v[140:143], v[164:167], v[72:75]
	v_mfma_f32_16x16x32_bf16 v[8:11], v[132:135], v[172:175], v[8:11]
	v_mfma_f32_16x16x32_bf16 v[16:19], v[140:143], v[172:175], v[16:19]
	v_mfma_f32_16x16x32_bf16 v[56:59], v[132:135], v[196:199], v[56:59]
	v_mfma_f32_16x16x32_bf16 v[60:63], v[140:143], v[196:199], v[60:63]
	v_mfma_f32_16x16x32_bf16 v[36:39], v[132:135], v[238:241], v[36:39]
	v_mfma_f32_16x16x32_bf16 v[44:47], v[140:143], v[238:241], v[44:47]
	s_setprio 0
	s_setprio 1
	v_mfma_f32_16x16x32_bf16 v[12:15], v[144:147], v[160:163], 0
	v_mfma_f32_16x16x32_bf16 v[20:23], v[152:155], v[160:163], 0
	v_mfma_f32_16x16x32_bf16 v[0:3], v[144:147], v[168:171], 0
	v_mfma_f32_16x16x32_bf16 v[4:7], v[152:155], v[168:171], 0
	v_mfma_f32_16x16x32_bf16 v[32:35], v[144:147], v[186:189], 0
	v_mfma_f32_16x16x32_bf16 v[40:43], v[152:155], v[186:189], 0
	v_mfma_f32_16x16x32_bf16 v[24:27], v[144:147], v[224:227], 0
	v_mfma_f32_16x16x32_bf16 v[28:31], v[152:155], v[224:227], 0
	v_mfma_f32_16x16x32_bf16 v[12:15], v[148:151], v[164:167], v[12:15]
	v_mfma_f32_16x16x32_bf16 v[20:23], v[156:159], v[164:167], v[20:23]
	v_mfma_f32_16x16x32_bf16 v[0:3], v[148:151], v[172:175], v[0:3]
	v_mfma_f32_16x16x32_bf16 v[4:7], v[156:159], v[172:175], v[4:7]
	v_mfma_f32_16x16x32_bf16 v[32:35], v[148:151], v[196:199], v[32:35]
	v_mfma_f32_16x16x32_bf16 v[40:43], v[156:159], v[196:199], v[40:43]
	v_mfma_f32_16x16x32_bf16 v[24:27], v[148:151], v[238:241], v[24:27]
	v_mfma_f32_16x16x32_bf16 v[28:31], v[156:159], v[238:241], v[28:31]
	s_setprio 0
	s_barrier
	s_add_i32 s75, s75, s62
	v_lshl_add_u64 v[190:191], s[82:83], 0, v[192:193]
	s_mov_b32 m0, s75
	ds_read_b128 v[160:163], v231 offset:16384
	ds_read_b128 v[164:167], v231 offset:17408
	ds_read_b128 v[168:171], v231 offset:18432
	ds_read_b128 v[172:175], v231 offset:19456
	ds_read_b128 v[186:189], v231 offset:20480
	ds_read_b128 v[196:199], v231 offset:21504
	ds_read_b128 v[224:227], v231 offset:22528
	ds_read_b128 v[238:241], v231 offset:23552
	global_load_lds_dwordx4 v[190:191], off
	s_add_i32 m0, s75, 0x2000
	v_lshl_add_u64 v[200:201], s[82:83], 0, v[176:177]
	s_add_u32 s82, s82, s80
	s_addc_u32 s83, s83, 0
	s_add_i32 s55, s55, s62
	global_load_lds_dwordx4 v[200:201], off
	v_lshl_add_u64 v[234:235], s[82:83], 0, v[192:193]
	s_mov_b32 m0, s55
	v_lshl_add_u64 v[242:243], s[82:83], 0, v[176:177]
	global_load_lds_dwordx4 v[234:235], off
	s_add_i32 m0, s55, 0x2000
	v_lshl_add_u64 v[244:245], s[52:53], 0, v[180:181]
	global_load_lds_dwordx4 v[242:243], off
	s_mov_b32 m0, s63
	v_lshl_add_u64 v[246:247], s[52:53], 0, v[178:179]
	global_load_lds_dwordx4 v[244:245], off
	s_mov_b32 m0, s64
	s_nop 0
	global_load_lds_dwordx4 v[246:247], off
	s_waitcnt vmcnt(8)
	s_waitcnt lgkmcnt(0)
	s_barrier
	s_setprio 1
	s_waitcnt lgkmcnt(0)
	v_mfma_f32_16x16x32_bf16 v[88:91], v[128:131], v[160:163], 0
	v_mfma_f32_16x16x32_bf16 v[92:95], v[136:139], v[160:163], 0
	v_mfma_f32_16x16x32_bf16 v[76:79], v[128:131], v[168:171], 0
	v_mfma_f32_16x16x32_bf16 v[84:87], v[136:139], v[168:171], 0
	v_mfma_f32_16x16x32_bf16 v[120:123], v[128:131], v[186:189], 0
	v_mfma_f32_16x16x32_bf16 v[124:127], v[136:139], v[186:189], 0
	v_mfma_f32_16x16x32_bf16 v[108:111], v[128:131], v[224:227], 0
	v_mfma_f32_16x16x32_bf16 v[116:119], v[136:139], v[224:227], 0
	v_mfma_f32_16x16x32_bf16 v[88:91], v[132:135], v[164:167], v[88:91]
	v_mfma_f32_16x16x32_bf16 v[92:95], v[140:143], v[164:167], v[92:95]
	v_mfma_f32_16x16x32_bf16 v[76:79], v[132:135], v[172:175], v[76:79]
	v_mfma_f32_16x16x32_bf16 v[84:87], v[140:143], v[172:175], v[84:87]
	v_mfma_f32_16x16x32_bf16 v[120:123], v[132:135], v[196:199], v[120:123]
	v_mfma_f32_16x16x32_bf16 v[124:127], v[140:143], v[196:199], v[124:127]
	v_mfma_f32_16x16x32_bf16 v[108:111], v[132:135], v[238:241], v[108:111]
	v_mfma_f32_16x16x32_bf16 v[116:119], v[140:143], v[238:241], v[116:119]
	s_setprio 0
	s_setprio 1
	v_mfma_f32_16x16x32_bf16 v[64:67], v[144:147], v[160:163], 0
	v_mfma_f32_16x16x32_bf16 v[80:83], v[152:155], v[160:163], 0
	v_mfma_f32_16x16x32_bf16 v[48:51], v[144:147], v[168:171], 0
	v_mfma_f32_16x16x32_bf16 v[52:55], v[152:155], v[168:171], 0
	v_mfma_f32_16x16x32_bf16 v[104:107], v[144:147], v[186:189], 0
	v_mfma_f32_16x16x32_bf16 v[112:115], v[152:155], v[186:189], 0
	v_mfma_f32_16x16x32_bf16 v[96:99], v[144:147], v[224:227], 0
	v_mfma_f32_16x16x32_bf16 v[100:103], v[152:155], v[224:227], 0
	v_mfma_f32_16x16x32_bf16 v[64:67], v[148:151], v[164:167], v[64:67]
	v_mfma_f32_16x16x32_bf16 v[80:83], v[156:159], v[164:167], v[80:83]
	v_mfma_f32_16x16x32_bf16 v[48:51], v[148:151], v[172:175], v[48:51]
	v_mfma_f32_16x16x32_bf16 v[52:55], v[156:159], v[172:175], v[52:55]
	v_mfma_f32_16x16x32_bf16 v[104:107], v[148:151], v[196:199], v[104:107]
	v_mfma_f32_16x16x32_bf16 v[112:115], v[156:159], v[196:199], v[112:115]
	v_mfma_f32_16x16x32_bf16 v[96:99], v[148:151], v[238:241], v[96:99]
	v_mfma_f32_16x16x32_bf16 v[100:103], v[156:159], v[238:241], v[100:103]
	s_setprio 0
	s_barrier
	s_add_i32 s55, 0, 0x18000
	s_add_i32 s75, 0, 0x1c000
	v_add_u32_e32 v140, s55, v203
	v_add_u32_e32 v156, s75, v203
	ds_read_b128 v[128:131], v140
	ds_read_b128 v[132:135], v140 offset:1024
	ds_read_b128 v[136:139], v140 offset:2048
	ds_read_b128 v[140:143], v140 offset:3072
	ds_read_b128 v[144:147], v156
	ds_read_b128 v[148:151], v156 offset:1024
	ds_read_b128 v[152:155], v156 offset:2048
	ds_read_b128 v[156:159], v156 offset:3072
	s_add_u32 s52, s52, s80
	s_addc_u32 s53, s53, 0
	s_mov_b32 m0, s65
	v_lshl_add_u64 v[248:249], s[52:53], 0, v[180:181]
	ds_read_b128 v[160:163], v231 offset:32768
	ds_read_b128 v[164:167], v231 offset:33792
	ds_read_b128 v[168:171], v231 offset:34816
	ds_read_b128 v[172:175], v231 offset:35840
	ds_read_b128 v[186:189], v231 offset:36864
	ds_read_b128 v[196:199], v231 offset:37888
	ds_read_b128 v[224:227], v231 offset:38912
	ds_read_b128 v[238:241], v231 offset:39936
	global_load_lds_dwordx4 v[248:249], off
	v_lshl_add_u64 v[248:249], s[52:53], 0, v[178:179]
	s_mov_b32 m0, s66
	s_nop 0
	global_load_lds_dwordx4 v[248:249], off
	s_waitcnt vmcnt(8)
	s_waitcnt lgkmcnt(0)
	s_barrier
	s_setprio 1
	s_waitcnt lgkmcnt(0)
	v_mfma_f32_16x16x32_bf16 v[68:71], v[128:131], v[160:163], v[68:71]
	v_mfma_f32_16x16x32_bf16 v[72:75], v[136:139], v[160:163], v[72:75]
	v_mfma_f32_16x16x32_bf16 v[8:11], v[128:131], v[168:171], v[8:11]
	v_mfma_f32_16x16x32_bf16 v[16:19], v[136:139], v[168:171], v[16:19]
	v_mfma_f32_16x16x32_bf16 v[56:59], v[128:131], v[186:189], v[56:59]
	v_mfma_f32_16x16x32_bf16 v[60:63], v[136:139], v[186:189], v[60:63]
	v_mfma_f32_16x16x32_bf16 v[36:39], v[128:131], v[224:227], v[36:39]
	v_mfma_f32_16x16x32_bf16 v[44:47], v[136:139], v[224:227], v[44:47]
	v_mfma_f32_16x16x32_bf16 v[68:71], v[132:135], v[164:167], v[68:71]
	v_mfma_f32_16x16x32_bf16 v[72:75], v[140:143], v[164:167], v[72:75]
	v_mfma_f32_16x16x32_bf16 v[8:11], v[132:135], v[172:175], v[8:11]
	v_mfma_f32_16x16x32_bf16 v[16:19], v[140:143], v[172:175], v[16:19]
	v_mfma_f32_16x16x32_bf16 v[56:59], v[132:135], v[196:199], v[56:59]
	v_mfma_f32_16x16x32_bf16 v[60:63], v[140:143], v[196:199], v[60:63]
	v_mfma_f32_16x16x32_bf16 v[36:39], v[132:135], v[238:241], v[36:39]
	v_mfma_f32_16x16x32_bf16 v[44:47], v[140:143], v[238:241], v[44:47]
	s_setprio 0
	s_setprio 1
	v_mfma_f32_16x16x32_bf16 v[12:15], v[144:147], v[160:163], v[12:15]
	v_mfma_f32_16x16x32_bf16 v[20:23], v[152:155], v[160:163], v[20:23]
	v_mfma_f32_16x16x32_bf16 v[0:3], v[144:147], v[168:171], v[0:3]
	v_mfma_f32_16x16x32_bf16 v[4:7], v[152:155], v[168:171], v[4:7]
	v_mfma_f32_16x16x32_bf16 v[32:35], v[144:147], v[186:189], v[32:35]
	v_mfma_f32_16x16x32_bf16 v[40:43], v[152:155], v[186:189], v[40:43]
	v_mfma_f32_16x16x32_bf16 v[24:27], v[144:147], v[224:227], v[24:27]
	v_mfma_f32_16x16x32_bf16 v[28:31], v[152:155], v[224:227], v[28:31]
	v_mfma_f32_16x16x32_bf16 v[12:15], v[148:151], v[164:167], v[12:15]
	v_mfma_f32_16x16x32_bf16 v[20:23], v[156:159], v[164:167], v[20:23]
	v_mfma_f32_16x16x32_bf16 v[0:3], v[148:151], v[172:175], v[0:3]
	v_mfma_f32_16x16x32_bf16 v[4:7], v[156:159], v[172:175], v[4:7]
	v_mfma_f32_16x16x32_bf16 v[32:35], v[148:151], v[196:199], v[32:35]
	v_mfma_f32_16x16x32_bf16 v[40:43], v[156:159], v[196:199], v[40:43]
	v_mfma_f32_16x16x32_bf16 v[24:27], v[148:151], v[238:241], v[24:27]
	v_mfma_f32_16x16x32_bf16 v[28:31], v[156:159], v[238:241], v[28:31]
	s_setprio 0
	s_barrier
	s_nop 0
	s_add_i32 s52, s55, s62
	v_lshl_add_u64 v[190:191], v[190:191], 0, s[2:3]
	s_mov_b32 m0, s52
	ds_read_b128 v[160:163], v231 offset:49152
	ds_read_b128 v[164:167], v231 offset:50176
	ds_read_b128 v[168:171], v231 offset:51200
	ds_read_b128 v[172:175], v231 offset:52224
	ds_read_b128 v[186:189], v231 offset:53248
	ds_read_b128 v[196:199], v231 offset:54272
	ds_read_b128 v[224:227], v231 offset:55296
	ds_read_b128 v[238:241], v231 offset:56320
	global_load_lds_dwordx4 v[190:191], off
	v_lshl_add_u64 v[190:191], v[200:201], 0, s[2:3]
	s_add_i32 m0, s52, 0x2000
	s_add_i32 s52, s75, s62
	global_load_lds_dwordx4 v[190:191], off
	v_lshl_add_u64 v[190:191], v[234:235], 0, s[2:3]
	s_mov_b32 m0, s52
	s_nop 0
	global_load_lds_dwordx4 v[190:191], off
	v_lshl_add_u64 v[190:191], v[242:243], 0, s[2:3]
	s_add_i32 m0, s52, 0x2000
	s_nop 0
	global_load_lds_dwordx4 v[190:191], off
	v_lshl_add_u64 v[190:191], v[244:245], 0, s[2:3]
	s_mov_b32 m0, s69
	s_nop 0
	global_load_lds_dwordx4 v[190:191], off
	v_lshl_add_u64 v[190:191], v[246:247], 0, s[2:3]
	s_mov_b32 m0, s70
	s_nop 0
	global_load_lds_dwordx4 v[190:191], off
	s_waitcnt vmcnt(8)
	s_waitcnt lgkmcnt(0)
	s_barrier
	s_setprio 1
	s_waitcnt lgkmcnt(0)
	v_mfma_f32_16x16x32_bf16 v[88:91], v[128:131], v[160:163], v[88:91]
	v_mfma_f32_16x16x32_bf16 v[92:95], v[136:139], v[160:163], v[92:95]
	v_mfma_f32_16x16x32_bf16 v[76:79], v[128:131], v[168:171], v[76:79]
	v_mfma_f32_16x16x32_bf16 v[84:87], v[136:139], v[168:171], v[84:87]
	v_mfma_f32_16x16x32_bf16 v[120:123], v[128:131], v[186:189], v[120:123]
	v_mfma_f32_16x16x32_bf16 v[124:127], v[136:139], v[186:189], v[124:127]
	v_mfma_f32_16x16x32_bf16 v[108:111], v[128:131], v[224:227], v[108:111]
	v_mfma_f32_16x16x32_bf16 v[116:119], v[136:139], v[224:227], v[116:119]
	v_mfma_f32_16x16x32_bf16 v[88:91], v[132:135], v[164:167], v[88:91]
	v_mfma_f32_16x16x32_bf16 v[92:95], v[140:143], v[164:167], v[92:95]
	v_mfma_f32_16x16x32_bf16 v[76:79], v[132:135], v[172:175], v[76:79]
	v_mfma_f32_16x16x32_bf16 v[84:87], v[140:143], v[172:175], v[84:87]
	v_mfma_f32_16x16x32_bf16 v[120:123], v[132:135], v[196:199], v[120:123]
	v_mfma_f32_16x16x32_bf16 v[124:127], v[140:143], v[196:199], v[124:127]
	v_mfma_f32_16x16x32_bf16 v[108:111], v[132:135], v[238:241], v[108:111]
	v_mfma_f32_16x16x32_bf16 v[116:119], v[140:143], v[238:241], v[116:119]
	s_setprio 0
	s_setprio 1
	v_mfma_f32_16x16x32_bf16 v[64:67], v[144:147], v[160:163], v[64:67]
	v_mfma_f32_16x16x32_bf16 v[80:83], v[152:155], v[160:163], v[80:83]
	v_mfma_f32_16x16x32_bf16 v[48:51], v[144:147], v[168:171], v[48:51]
	v_mfma_f32_16x16x32_bf16 v[52:55], v[152:155], v[168:171], v[52:55]
	v_mfma_f32_16x16x32_bf16 v[104:107], v[144:147], v[186:189], v[104:107]
	v_mfma_f32_16x16x32_bf16 v[112:115], v[152:155], v[186:189], v[112:115]
	v_mfma_f32_16x16x32_bf16 v[96:99], v[144:147], v[224:227], v[96:99]
	v_mfma_f32_16x16x32_bf16 v[100:103], v[152:155], v[224:227], v[100:103]
	v_mfma_f32_16x16x32_bf16 v[64:67], v[148:151], v[164:167], v[64:67]
	v_mfma_f32_16x16x32_bf16 v[80:83], v[156:159], v[164:167], v[80:83]
	v_mfma_f32_16x16x32_bf16 v[48:51], v[148:151], v[172:175], v[48:51]
	v_mfma_f32_16x16x32_bf16 v[52:55], v[156:159], v[172:175], v[52:55]
	v_mfma_f32_16x16x32_bf16 v[104:107], v[148:151], v[196:199], v[104:107]
	v_mfma_f32_16x16x32_bf16 v[112:115], v[156:159], v[196:199], v[112:115]
	v_mfma_f32_16x16x32_bf16 v[96:99], v[148:151], v[238:241], v[96:99]
	v_mfma_f32_16x16x32_bf16 v[100:103], v[156:159], v[238:241], v[100:103]
	s_setprio 0
	s_barrier
	s_add_u32 s51, s51, 0x100
	s_addc_u32 s74, s74, 0
	s_add_u32 s12, s12, 0x100
	s_addc_u32 s13, s13, 0
	s_cmp_ge_u32 s54, s72
	s_mov_b32 s52, s54
	s_cbranch_scc0 .LBB0_668
	s_branch .Lpeel_exit_668
